# P8 row-tile order reversed within each XCD group so P9 reads the most recently written F rows first (MALL retention)
# speedup vs baseline: 1.0150x; 1.0080x over previous
.LBB0_885:
	s_cmp_lt_i32 s82, 9
	s_cselect_b64 s[6:7], -1, 0
	s_add_u32 s4, s78, 0x8000000
	s_addc_u32 s5, s79, 0
	s_and_b64 s[6:7], s[6:7], s[0:1]
	s_andn2_b64 vcc, exec, s[6:7]
	s_cbranch_vccnz .LBB0_902
	s_cmpk_gt_i32 s2, 0x9ff
	v_readfirstlane_b32 s8, v210
	s_cbranch_scc1 .LBB0_902
	v_lshlrev_b32_e32 v1, 4, v210
	v_add_u32_e32 v8, 0x2000, v1
	v_lshrrev_b32_e32 v2, 7, v8
	v_bfe_u32 v11, v210, 2, 4
	s_movk_i32 s0, 0xf0
	v_lshrrev_b32_e32 v0, 3, v210
	v_and_or_b32 v2, v2, s0, v11
	s_movk_i32 s0, 0x70
	s_ashr_i32 s35, s2, 31
	v_and_or_b32 v0, v0, s0, v11
	s_lshr_b32 s0, s35, 29
	s_add_i32 s0, s2, s0
	s_lshr_b32 s12, s8, 6
	s_ashr_i32 s9, s0, 3
	s_and_b32 s0, s0, -8
	s_lshr_b32 s1, s8, 8
	s_lshl_b32 s3, s12, 10
	s_sub_i32 s0, s2, s0
	s_cmp_lt_i32 s0, 0
	s_movk_i32 s38, 0x141
	s_cselect_b32 s10, s38, 0x140
	s_mul_i32 s0, s0, s10
	s_add_i32 s0, s0, s9
	s_ashr_i32 s9, s0, 31
	s_lshr_b32 s9, s9, 26
	s_add_i32 s9, s0, s9
	s_ashr_i32 s10, s9, 6
	s_andn2_b32 s9, s9, 63
	s_sub_i32 s9, s0, s9
	s_bfe_i32 s0, s9, 0x80000
	s_bfe_u32 s0, s0, 0x2000d
	s_add_i32 s11, s9, s0
	s_bfe_i32 s0, s11, 0x80000
	s_and_b32 s11, s11, 0xfc
	s_sub_i32 s9, s9, s11
	s_lshl_b32 s10, s10, 2
	s_sext_i32_i16 s0, s0
	s_sext_i32_i8 s9, s9
	s_lshr_b32 s0, s0, 2
	s_add_i32 s26, s10, s9
	s_mul_i32 s98, s26, 0xccd
	s_lshr_b32 s98, s98, 16
	s_mul_i32 s98, s98, 40
	s_sub_i32 s26, s98, s26
	s_add_i32 s26, s26, 19
	s_ashr_i32 s27, s26, 31
	s_bfe_i64 s[14:15], s[0:1], 0x100000
	v_and_b32_e32 v3, 32, v210
	s_lshl_b64 s[10:11], s[26:27], 19
	s_lshl_b64 s[14:15], s[14:15], 19
	v_bitop3_b32 v9, v1, v3, 48 bitop3:0x6c
	s_waitcnt lgkmcnt(0)
	v_and_b32_e32 v10, 64, v210
	s_add_u32 s30, s70, s14
	v_or_b32_e32 v1, v9, v10
	s_addc_u32 s31, s71, s15
	s_add_i32 s27, s3, 0
	v_lshl_or_b32 v130, v0, 11, v1
	s_add_i32 m0, s27, 0x10000
	v_lshl_or_b32 v128, v2, 11, v1
	global_load_lds_dwordx4 v130, s[30:31]
	s_add_i32 m0, s27, 0x12000
	s_add_u32 s14, s30, 0x40000
	global_load_lds_dwordx4 v128, s[30:31]
	s_addc_u32 s15, s31, 0
	s_add_i32 m0, s27, 0x14000
	v_mov_b32_e32 v133, 0
	global_load_lds_dwordx4 v130, s[14:15]
	s_add_i32 m0, s27, 0x16000
	s_add_u32 s28, s22, s10
	s_addc_u32 s29, s23, s11
	s_add_i32 s39, s27, 0x2000
	global_load_lds_dwordx4 v128, s[14:15]
	s_mov_b32 m0, s27
	s_add_u32 s10, s28, 0x40000
	global_load_lds_dwordx4 v130, s[28:29]
	s_mov_b32 m0, s39
	s_addc_u32 s11, s29, 0
	s_add_i32 s40, s27, 0x4000
	global_load_lds_dwordx4 v128, s[28:29]
	s_mov_b32 m0, s40
	s_add_i32 s41, s27, 0x6000
	global_load_lds_dwordx4 v130, s[10:11]
	s_mov_b32 m0, s41
	v_mov_b32_e32 v131, v133
	global_load_lds_dwordx4 v128, s[10:11]
	v_mov_b32_e32 v129, v133
	s_cmp_eq_u32 s1, 1
	s_mov_b32 s9, 0
	s_mov_b32 s42, 0x10000
	v_lshl_add_u64 v[6:7], s[30:31], 0, v[130:131]
	v_lshl_add_u64 v[4:5], s[30:31], 0, v[128:129]
	v_lshl_add_u64 v[0:1], s[28:29], 0, v[130:131]
	s_cselect_b64 s[10:11], -1, 0
	s_cmp_lg_u32 s1, 1
	v_lshl_add_u64 v[2:3], s[28:29], 0, v[128:129]
	s_cbranch_scc1 .LBB0_889
	s_barrier

.LBB0_892:
	s_add_i32 s60, s60, 1
	s_mul_i32 s0, s60, s45
	s_mul_hi_u32 s1, s60, s33
	s_add_i32 s1, s1, s0
	s_mul_i32 s0, s60, s33
	s_add_u32 s20, s0, s2
	s_addc_u32 s21, s1, s35
	v_cmp_gt_i64_e32 vcc, s[20:21], v[140:141]
	v_cmp_lt_i64_e64 s[0:1], s[20:21], v[138:139]
	s_cbranch_vccnz .LBB0_894
	s_ashr_i32 s16, s20, 31
	s_lshr_b32 s16, s16, 29
	s_add_i32 s16, s20, s16
	s_ashr_i32 s17, s16, 3
	s_and_b32 s16, s16, -8
	s_sub_i32 s16, s20, s16
	s_cmp_lt_i32 s16, 0
	s_cselect_b32 s18, s38, 0x140
	s_mul_i32 s16, s16, s18
	s_add_i32 s16, s16, s17
	s_ashr_i32 s17, s16, 31
	s_lshr_b32 s17, s17, 26
	s_add_i32 s17, s16, s17
	s_ashr_i32 s18, s17, 6
	s_lshl_b32 s18, s18, 2
	s_sub_i32 s19, 0xa0, s18
	s_min_i32 s19, s19, 4
	s_abs_i32 s20, s19
	v_cvt_f32_u32_e32 v0, s20
	s_sub_i32 s24, 0, s20
	s_andn2_b32 s17, s17, 63
	s_sub_i32 s17, s16, s17
	v_rcp_iflag_f32_e32 v0, v0
	s_abs_i32 s16, s17
	s_xor_b32 s21, s17, s19
	s_ashr_i32 s21, s21, 31
	v_mul_f32_e32 v0, 0x4f7ffffe, v0
	v_cvt_u32_f32_e32 v0, v0
	s_nop 0
	v_readfirstlane_b32 s25, v0
	s_mul_i32 s24, s24, s25
	s_mul_hi_u32 s24, s25, s24
	s_add_i32 s25, s25, s24
	s_mul_hi_u32 s24, s16, s25
	s_mul_i32 s25, s24, s20
	s_sub_i32 s16, s16, s25
	s_add_i32 s36, s24, 1
	s_sub_i32 s25, s16, s20
	s_cmp_ge_u32 s16, s20
	s_cselect_b32 s24, s36, s24
	s_cselect_b32 s16, s25, s16
	s_add_i32 s25, s24, 1
	s_cmp_ge_u32 s16, s20
	s_cselect_b32 s16, s25, s24
	s_xor_b32 s16, s16, s21
	s_sub_i32 s16, s16, s21
	s_mul_i32 s19, s16, s19
	s_sub_i32 s17, s17, s19
	s_add_i32 s18, s18, s17
	s_mul_i32 s98, s18, 0xccd
	s_lshr_b32 s98, s98, 16
	s_mul_i32 s98, s98, 40
	s_sub_i32 s18, s98, s18
	s_add_i32 s18, s18, 19
